# attention selected loop: K/V fragment LDS prefetch + hoisted addresses + L2 warm-up of following block
# speedup vs baseline: 1.0007x; 1.0007x over previous
.LBB0_1269:
	s_xor_b64 s[0:1], s[0:1], -1
	s_andn2_b64 vcc, exec, s[0:1]
	s_waitcnt vmcnt(0)
	ds_write_b128 v163, v[68:71]
	ds_write_b16 v167, v96 offset:9216
	ds_write_b16_d16_hi v167, v96 offset:9352
	ds_write_b16 v167, v97 offset:9488
	ds_write_b16_d16_hi v167, v97 offset:9624
	ds_write_b16 v167, v98 offset:9760
	ds_write_b16_d16_hi v167, v98 offset:9896
	ds_write_b16 v167, v99 offset:10032
	ds_write_b16_d16_hi v167, v99 offset:10168
	s_cbranch_vccnz .LBB0_1271
	s_mov_b32 s55, s49
	s_lshl_b64 s[0:1], s[54:55], 13
	s_add_u32 s34, s14, s0
	s_addc_u32 s35, s15, s1
	s_add_u32 s0, s16, s0
	v_mov_b32_e32 v73, v177
	s_addc_u32 s1, s17, s1
	v_lshl_add_u64 v[0:1], s[34:35], 0, v[72:73]
	v_lshl_add_u64 v[2:3], v[120:121], 1, s[0:1]
	v_lshl_add_u64 v[0:1], v[124:125], 1, v[0:1]
	global_load_dwordx4 v[68:71], v[2:3], off
	global_load_dwordx4 v[96:99], v[0:1], off
	s_add_u32 s0, s0, 0x2000
	s_addc_u32 s1, s1, 0
	s_add_u32 s34, s34, 0x2000
	s_addc_u32 s35, s35, 0
	v_lshl_add_u64 v[2:3], v[120:121], 1, s[0:1]
	v_lshl_add_u64 v[0:1], s[34:35], 0, v[72:73]
	v_lshl_add_u64 v[0:1], v[124:125], 1, v[0:1]
	global_load_dword v251, v[2:3], off
	global_load_dword v251, v[0:1], off
.LBB0_1271:
	s_waitcnt lgkmcnt(0)
	s_barrier
	s_cmp_lt_i32 s86, 0
	s_mov_b32 s34, 0
	s_cbranch_scc1 .LBB0_1296
	v_mov_b32_e32 v73, v177
	v_readlane_b32 s0, v255, 3
	v_lshl_add_u64 v[0:1], s[14:15], 0, v[72:73]
	v_mov_b32_e32 v73, 0
	v_mul_f32_e32 v82, s0, v131
	s_mov_b32 s2, s30
	v_mul_lo_u32 v248, v156, s64
	v_mul_lo_u32 v223, v156, s43
	v_lshlrev_b32_e32 v249, 2, v123
	v_lshl_add_u32 v248, v123, 2, v248
	v_lshl_add_u32 v223, v123, 4, v223
	v_cvt_f32_i32_e32 v249, v249
	v_lshlrev_b32_e32 v248, 1, v248
	v_add_u32_e32 v248, 0x2000, v248
	s_mov_b32 s30, s65
	s_mov_b32 s65, s37
	s_mov_b32 s37, s47
	s_mov_b32 s47, s46
	v_lshl_add_u64 v[76:77], v[124:125], 1, v[0:1]
	v_fmac_f32_e32 v82, v134, v164
	v_mov_b32_e32 v78, v134
	v_mov_b32_e32 v79, v134
	v_mov_b32_e32 v80, v134
	v_mov_b32_e32 v81, v134
	s_mov_b32 s35, 0
	v_mov_b32_e32 v0, 0
	v_mov_b32_e32 v1, v73
	v_mov_b32_e32 v2, v73
	v_mov_b32_e32 v3, v73
	v_mov_b32_e32 v4, v73
	v_mov_b32_e32 v5, v73
	v_mov_b32_e32 v6, v73
	v_mov_b32_e32 v7, v73
	v_mov_b32_e32 v8, v73
	v_mov_b32_e32 v9, v73
	v_mov_b32_e32 v10, v73
	v_mov_b32_e32 v11, v73
	v_mov_b32_e32 v12, v73
	v_mov_b32_e32 v13, v73
	v_mov_b32_e32 v14, v73
	v_mov_b32_e32 v15, v73
	v_mov_b32_e32 v16, 0
	v_mov_b32_e32 v17, v73
	v_mov_b32_e32 v18, v73
	v_mov_b32_e32 v19, v73
	v_mov_b32_e32 v20, v73
	v_mov_b32_e32 v21, v73
	v_mov_b32_e32 v22, v73
	v_mov_b32_e32 v23, v73
	v_mov_b32_e32 v24, v73
	v_mov_b32_e32 v25, v73
	v_mov_b32_e32 v26, v73
	v_mov_b32_e32 v27, v73
	v_mov_b32_e32 v28, v73
	v_mov_b32_e32 v29, v73
	v_mov_b32_e32 v30, v73
	v_mov_b32_e32 v31, v73

.LBB0_1286:
	s_cmp_gt_i32 s46, s33
	s_cselect_b64 s[86:87], -1, 0
	s_and_b64 vcc, exec, s[86:87]
	s_cbranch_vccnz .LBB0_1290
	s_andn2_b32 s14, 1, s34
	s_mulk_i32 s14, 0x4800
	s_add_i32 s14, s14, 0
	v_add3_u32 v32, s14, v161, v162
	s_waitcnt vmcnt(2)
	ds_write_b128 v32, v[68:71]
	v_add3_u32 v32, s14, v165, v166
	s_andn2_b64 vcc, exec, s[0:1]
	ds_write_b16 v32, v96 offset:9216
	ds_write_b16_d16_hi v32, v96 offset:9352
	ds_write_b16 v32, v97 offset:9488
	ds_write_b16_d16_hi v32, v97 offset:9624
	ds_write_b16 v32, v98 offset:9760
	ds_write_b16_d16_hi v32, v98 offset:9896
	ds_write_b16 v32, v99 offset:10032
	ds_write_b16_d16_hi v32, v99 offset:10168
	s_cbranch_vccnz .LBB0_1290
	s_ashr_i32 s55, s54, 31
	s_lshl_b64 s[0:1], s[54:55], 13
	v_lshl_add_u64 v[32:33], v[74:75], 0, s[0:1]
	global_load_dwordx4 v[68:71], v[32:33], off
	s_and_b64 vcc, exec, s[12:13]
	s_cbranch_vccnz .LBB0_1290
	s_lshl_b64 s[0:1], s[54:55], 12
	v_lshl_add_u64 v[32:33], s[0:1], 1, v[76:77]
	global_load_dwordx4 v[96:99], v[32:33], off
	s_add_u32 s0, s0, 0x1000
	s_addc_u32 s1, s1, 0
	v_lshl_add_u64 v[32:33], s[0:1], 1, v[74:75]
	global_load_dword v251, v[32:33], off
	v_lshl_add_u64 v[32:33], s[0:1], 1, v[76:77]
	global_load_dword v251, v[32:33], off
.LBB0_1290:
	s_ashr_i32 s0, s35, 5
	s_cmp_lt_u32 s35, 32
	s_cselect_b64 vcc, -1, 0
	s_cmp_eq_u32 s0, 1
	s_cselect_b64 s[14:15], -1, 0
	s_cmp_eq_u32 s0, 2
	s_cselect_b64 s[16:17], -1, 0
	s_waitcnt lgkmcnt(9)
	v_cndmask_b32_e64 v32, v67, v66, s[16:17]
	v_cndmask_b32_e64 v32, v32, v65, s[14:15]
	v_cndmask_b32_e32 v32, v32, v64, vcc
	s_and_b32 s0, s35, 31
	v_lshrrev_b32_e32 v33, s35, v32
	v_and_b32_e32 v33, 1, v33
	v_bfe_u32 v32, v32, s0, 1
	v_cmp_eq_u32_e64 s[14:15], 1, v33
	v_cmp_ne_u32_e32 vcc, 0, v32
	s_cbranch_vccz .LBB0_1294
	s_bitcmp1_b32 s34, 0
	s_cselect_b32 s0, 0x4800, 0
	s_add_i32 s0, s0, 0
	s_sub_i32 s1, s35, s33
	v_add_u32_e32 v83, s0, v223
	s_lshl_b32 s1, s1, 6
	v_add_u32_e32 v238, s0, v248
	ds_read_b128 v[48:51], v83
	ds_read_b128 v[84:87], v83 offset:4608
	ds_read_b128 v[240:243], v83 offset:32
	ds_read_b128 v[244:247], v83 offset:4640
	ds_read_b128 v[140:143], v83 offset:64
	ds_read_b128 v[144:147], v83 offset:4672
	ds_read_b128 v[92:95], v83 offset:96
	ds_read_b128 v[116:119], v83 offset:4704
	v_cvt_f32_i32_e32 v32, s1
	v_add_u32_e32 v239, 0x1100, v238
	v_mov_b32_e32 v135, v134
	s_cmp_lg_u32 s35, s33
	v_fma_f32 v32, v134, v32, -v82
	v_cndmask_b32_e64 v88, v237, v32, s[14:15]
	v_fmac_f32_e32 v88, v134, v249
	v_fma_f32 v32, 0, v134, v88
	v_add_f32_e32 v33, v134, v88
	v_pk_fma_f32 v[34:35], v[78:79], s[72:73], v[88:89] op_sel_hi:[1,1,0]
	v_pk_fma_f32 v[36:37], v[78:79], s[52:53], v[88:89] op_sel_hi:[1,1,0]
	v_pk_fma_f32 v[38:39], v[78:79], s[56:57], v[88:89] op_sel_hi:[1,1,0]
	v_pk_fma_f32 v[40:41], v[78:79], s[76:77], v[88:89] op_sel_hi:[1,1,0]
	v_pk_fma_f32 v[42:43], v[78:79], s[92:93], v[88:89] op_sel_hi:[1,1,0]
	v_pk_fma_f32 v[44:45], v[78:79], s[62:63], v[88:89] op_sel_hi:[1,1,0]
	v_pk_fma_f32 v[46:47], v[78:79], s[74:75], v[88:89] op_sel_hi:[1,1,0]
	v_pk_fma_f32 v[62:63], v[134:135], s[68:69], v[88:89] op_sel_hi:[1,1,0]
	v_pk_fma_f32 v[60:61], v[134:135], s[82:83], v[88:89] op_sel_hi:[1,1,0]
	s_waitcnt lgkmcnt(7)
	v_mfma_f32_32x32x16_bf16 v[32:47], v[48:51], v[100:103], v[32:47]
	v_fma_f32 v58, v134, s90, v88
	v_fma_f32 v59, v135, s91, v88
	v_fma_f32 v56, v134, s70, v88
	v_fma_f32 v57, v135, s71, v88
	v_fma_f32 v54, v134, s60, v88
	v_fma_f32 v55, v135, s61, v88
	v_pk_fma_f32 v[52:53], v[134:135], s[78:79], v[88:89] op_sel_hi:[1,1,0]
	v_pk_fma_f32 v[50:51], v[134:135], s[84:85], v[88:89] op_sel_hi:[1,1,0]
	v_pk_fma_f32 v[48:49], v[80:81], s[94:95], v[88:89] op_sel_hi:[1,1,0]
	s_waitcnt lgkmcnt(6)
	s_nop 0
	v_mfma_f32_32x32x16_bf16 v[48:63], v[84:87], v[100:103], v[48:63]
	s_waitcnt lgkmcnt(5)
	v_mfma_f32_32x32x16_bf16 v[32:47], v[240:243], v[104:107], v[32:47]
	s_waitcnt lgkmcnt(4)
	v_mfma_f32_32x32x16_bf16 v[48:63], v[244:247], v[104:107], v[48:63]
	s_waitcnt lgkmcnt(3)
	v_mfma_f32_32x32x16_bf16 v[32:47], v[140:143], v[108:111], v[32:47]
	s_waitcnt lgkmcnt(2)
	v_mfma_f32_32x32x16_bf16 v[48:63], v[144:147], v[108:111], v[48:63]
	s_waitcnt lgkmcnt(1)
	v_mfma_f32_32x32x16_bf16 v[32:47], v[92:95], v[112:115], v[32:47]
	s_waitcnt lgkmcnt(0)
	v_mfma_f32_32x32x16_bf16 v[48:63], v[116:119], v[112:115], v[48:63]
	s_cbranch_scc1 .LBB0_1293
	v_mov_b32_e32 v83, v123
	s_nop 0
	v_lshlrev_b32_e32 v83, 2, v83
	v_sub_u32_e32 v83, v158, v83
	v_cmp_lt_i32_e32 vcc, -1, v83
	s_nop 2
	v_cndmask_b32_e32 v32, v237, v32, vcc
	v_cmp_lt_i32_e32 vcc, 31, v83
	s_nop 1
	v_cndmask_b32_e32 v48, v237, v48, vcc
	v_cmp_lt_i32_e32 vcc, 0, v83
	s_nop 1
	v_cndmask_b32_e32 v33, v237, v33, vcc
	v_cmp_lt_i32_e32 vcc, 32, v83
	s_nop 1
	v_cndmask_b32_e32 v49, v237, v49, vcc
	v_cmp_lt_i32_e32 vcc, 1, v83
	s_nop 1
	v_cndmask_b32_e32 v34, v237, v34, vcc
	v_cmp_lt_i32_e32 vcc, 33, v83
	s_nop 1
	v_cndmask_b32_e32 v50, v237, v50, vcc
	v_cmp_lt_i32_e32 vcc, 2, v83
	s_nop 1
	v_cndmask_b32_e32 v35, v237, v35, vcc
	v_cmp_lt_i32_e32 vcc, 34, v83
	s_nop 1
	v_cndmask_b32_e32 v51, v237, v51, vcc
	v_cmp_lt_i32_e32 vcc, 7, v83
	s_nop 1
	v_cndmask_b32_e32 v36, v237, v36, vcc
	v_cmp_lt_i32_e32 vcc, 39, v83
	s_nop 1
	v_cndmask_b32_e32 v52, v237, v52, vcc
	v_cmp_lt_i32_e32 vcc, 8, v83
	s_nop 1
	v_cndmask_b32_e32 v37, v237, v37, vcc
	v_cmp_lt_i32_e32 vcc, 40, v83
	s_nop 1
	v_cndmask_b32_e32 v53, v237, v53, vcc
	v_cmp_lt_i32_e32 vcc, 9, v83
	s_nop 1
	v_cndmask_b32_e32 v38, v237, v38, vcc
	v_cmp_lt_i32_e32 vcc, 41, v83
	s_nop 1
	v_cndmask_b32_e32 v54, v237, v54, vcc
	v_cmp_lt_i32_e32 vcc, 10, v83
	s_nop 1
	v_cndmask_b32_e32 v39, v237, v39, vcc
	v_cmp_lt_i32_e32 vcc, 42, v83
	s_nop 1
	v_cndmask_b32_e32 v55, v237, v55, vcc
	v_cmp_lt_i32_e32 vcc, 15, v83
	s_nop 1
	v_cndmask_b32_e32 v40, v237, v40, vcc
	v_cmp_lt_i32_e32 vcc, 47, v83
	s_nop 1
	v_cndmask_b32_e32 v56, v237, v56, vcc
	v_cmp_lt_i32_e32 vcc, 16, v83
	s_nop 1
	v_cndmask_b32_e32 v41, v237, v41, vcc
	v_cmp_lt_i32_e32 vcc, 48, v83
	s_nop 1
	v_cndmask_b32_e32 v57, v237, v57, vcc
	v_cmp_lt_i32_e32 vcc, 17, v83
	s_nop 1
	v_cndmask_b32_e32 v42, v237, v42, vcc
	v_cmp_lt_i32_e32 vcc, 49, v83
	s_nop 1
	v_cndmask_b32_e32 v58, v237, v58, vcc
	v_cmp_lt_i32_e32 vcc, 18, v83
	s_nop 1
	v_cndmask_b32_e32 v43, v237, v43, vcc
	v_cmp_lt_i32_e32 vcc, 50, v83
	s_nop 1
	v_cndmask_b32_e32 v59, v237, v59, vcc
	v_cmp_lt_i32_e32 vcc, 23, v83
	s_nop 1
	v_cndmask_b32_e32 v44, v237, v44, vcc
	v_cmp_lt_i32_e32 vcc, 55, v83
	s_nop 1
	v_cndmask_b32_e32 v60, v237, v60, vcc
	v_cmp_lt_i32_e32 vcc, 24, v83
	s_nop 1
	v_cndmask_b32_e32 v45, v237, v45, vcc
	v_cmp_lt_i32_e32 vcc, 56, v83
	s_nop 1
	v_cndmask_b32_e32 v61, v237, v61, vcc
	v_cmp_lt_i32_e32 vcc, 25, v83
	s_nop 1
	v_cndmask_b32_e32 v46, v237, v46, vcc
	v_cmp_lt_i32_e32 vcc, 57, v83
	s_nop 1
	v_cndmask_b32_e32 v62, v237, v62, vcc
	v_cmp_lt_i32_e32 vcc, 26, v83
	s_nop 1
	v_cndmask_b32_e32 v47, v237, v47, vcc
	v_cmp_lt_i32_e32 vcc, 58, v83
	s_nop 1
	v_cndmask_b32_e32 v63, v237, v63, vcc
.LBB0_1293:
	s_nop 7
	v_exp_f32_e32 v84, v32
	v_exp_f32_e32 v85, v33
	ds_read2_b64 v[240:243], v238 offset0:132 offset1:134
	ds_read2_b64 v[244:247], v239 offset0:132 offset1:134
	v_exp_f32_e32 v86, v34
	v_exp_f32_e32 v87, v35
	v_exp_f32_e32 v88, v36
	ds_read2_b64 v[32:35], v238 offset0:128 offset1:130
	v_exp_f32_e32 v89, v37
	v_exp_f32_e32 v90, v38
	v_exp_f32_e32 v91, v39
	ds_read2_b64 v[36:39], v239 offset0:128 offset1:130
	v_exp_f32_e32 v50, v50
	v_exp_f32_e32 v51, v51
	v_exp_f32_e32 v92, v40
	v_exp_f32_e32 v93, v41
	v_exp_f32_e32 v94, v42
	v_exp_f32_e32 v95, v43
	v_pk_add_f32 v[118:119], v[86:87], v[50:51]
	v_cvt_pk_bf16_f32 v40, v84, v85
	v_cvt_pk_bf16_f32 v41, v86, v87
	v_cvt_pk_bf16_f32 v42, v88, v89
	v_cvt_pk_bf16_f32 v43, v90, v91
	v_exp_f32_e32 v44, v44
	s_waitcnt lgkmcnt(1)
	v_mfma_f32_32x32x16_bf16 v[16:31], v[32:35], v[40:43], v[16:31]
	ds_read2_b64 v[32:35], v238 offset0:136 offset1:138
	v_exp_f32_e32 v45, v45
	v_exp_f32_e32 v46, v46
	s_waitcnt lgkmcnt(1)
	v_mfma_f32_32x32x16_bf16 v[0:15], v[36:39], v[40:43], v[0:15]
	ds_read2_b64 v[36:39], v239 offset0:136 offset1:138
	v_exp_f32_e32 v62, v62
	v_exp_f32_e32 v47, v47
	v_exp_f32_e32 v63, v63
	v_cvt_pk_bf16_f32 v40, v92, v93
	v_cvt_pk_bf16_f32 v41, v94, v95
	v_cvt_pk_bf16_f32 v42, v44, v45
	v_pk_add_f32 v[138:139], v[46:47], v[62:63]
	v_cvt_pk_bf16_f32 v43, v46, v47
	v_exp_f32_e32 v48, v48
	s_waitcnt lgkmcnt(2)
	v_mfma_f32_32x32x16_bf16 v[16:31], v[240:243], v[40:43], v[16:31]
	ds_read2_b64 v[240:243], v238 offset0:140 offset1:142
	v_exp_f32_e32 v49, v49
	v_exp_f32_e32 v52, v52
	s_waitcnt lgkmcnt(3)
	v_mfma_f32_32x32x16_bf16 v[0:15], v[244:247], v[40:43], v[0:15]
	ds_read2_b64 v[244:247], v239 offset0:140 offset1:142
	v_exp_f32_e32 v53, v53
	v_exp_f32_e32 v54, v54
	v_exp_f32_e32 v55, v55
	v_pk_add_f32 v[144:145], v[84:85], v[48:49]
	v_cvt_pk_bf16_f32 v40, v48, v49
	v_cvt_pk_bf16_f32 v41, v50, v51
	v_cvt_pk_bf16_f32 v42, v52, v53
	v_cvt_pk_bf16_f32 v43, v54, v55
	v_exp_f32_e32 v56, v56
	s_waitcnt lgkmcnt(3)
	v_mfma_f32_32x32x16_bf16 v[16:31], v[32:35], v[40:43], v[16:31]
	v_exp_f32_e32 v57, v57
	v_exp_f32_e32 v58, v58
	s_waitcnt lgkmcnt(2)
	v_mfma_f32_32x32x16_bf16 v[0:15], v[36:39], v[40:43], v[0:15]
	v_exp_f32_e32 v59, v59
	v_exp_f32_e32 v60, v60
	v_exp_f32_e32 v61, v61
	v_cvt_pk_bf16_f32 v40, v56, v57
	v_cvt_pk_bf16_f32 v41, v58, v59
	v_cvt_pk_bf16_f32 v43, v62, v63
	v_cvt_pk_bf16_f32 v42, v60, v61
	v_pk_add_f32 v[116:117], v[94:95], v[58:59]
	v_pk_add_f32 v[140:141], v[90:91], v[54:55]
	s_waitcnt lgkmcnt(1)
	v_mfma_f32_32x32x16_bf16 v[16:31], v[240:243], v[40:43], v[16:31]
	v_add_f32_e64 v142, v92, v56
	v_add_f32_e64 v143, v93, v57
	v_add_f32_e64 v146, v44, v60
	v_add_f32_e64 v147, v45, v61
	v_add_f32_e64 v84, v88, v52
	v_add_f32_e64 v85, v89, v53
	v_pk_add_f32 v[46:47], v[144:145], v[142:143]
	v_pk_add_f32 v[44:45], v[84:85], v[146:147]
	v_pk_add_f32 v[32:33], v[140:141], v[138:139]
	v_pk_add_f32 v[34:35], v[118:119], v[116:117]
	s_waitcnt lgkmcnt(0)
	v_mfma_f32_32x32x16_bf16 v[0:15], v[244:247], v[40:43], v[0:15]
	v_add_f32_e64 v32, v34, v32
	v_add_f32_e64 v33, v35, v33
	v_add_f32_e64 v34, v46, v44
	v_add_f32_e64 v35, v47, v45
	v_add_f32_e64 v32, v34, v32
	v_add_f32_e64 v33, v35, v33
	v_add_f32_e32 v32, v32, v33
	v_add_f32_e32 v73, v73, v32
